# attention work queue per block group (batch stays on one XCD) on top of the peel/noinv version
# speedup vs baseline: 1.0072x; 1.0072x over previous
; #define LAS __attribute__((address_space(3)))
; __device__ __forceinline__ void attn_phase(const Params& p, LAS unsigned char* lds) {
;     const int tid = threadIdx.x, lane = tid & 63, w = __builtin_amdgcn_readfirstlane(tid >> 6), fr = lane & 15, fq = lane >> 4;
;     LAS unsigned char* Ks = lds;
;     LAS unsigned char* Vs = lds + 73728;
;     LAS float* rp = (LAS float*)(lds + 147456);
;     volatile LAS unsigned* slot = (volatile LAS unsigned*)(lds + 147456 + 2048);
;     const bf16_t* QH = (const bf16_t*)(p.ws + WS_QK); const bf16_t* KH = (const bf16_t*)(p.ws + WS_QK + (16u << 20)); const bf16_t* VTA = (const bf16_t*)(p.ws + WS_VTA);
;     bf16_t* YCAT = (bf16_t*)(p.ws + WS_YCAT); float* SSQNA = (float*)(p.ws + WS_SSQ1 + 512 * 1024);
;     const float sc2 = 0.125f * 1.4426950408889634f;
;     unsigned* ctr = (unsigned*)(p.ws + WS_BAR) + 3584;
;     const int ri = w >> 2, qb = w & 3, q0 = qb * 16, kc0 = min(max(q0 - 8, 0), 32);
;     const int kperm = 8 * (fr >> 2) + (fr & 3);
;     for (;;) {
;         __syncthreads();
;         if (tid == 0) slot[0] = __hip_atomic_fetch_add(ctr, 1u, __ATOMIC_RELAXED, __HIP_MEMORY_SCOPE_AGENT);
;         __syncthreads();
;         const int item = (int)slot[0];
;         if (item >= 1024) break;
;         const int b = item >> 7, h = (item >> 4) & 7, r0 = (item & 15) * 2, R0 = min(max(r0 - 4, 0), 24);
;         const int r = r0 + ri, rs = min(max(r - 4, 0), 24), j0 = rs - R0;
;         const int tq = b * SEQ + r * 64 + q0 + fr;
;         const bf16_t* qp = QH + ((size_t)(b * 8 + h) * SEQ + r * 64 + q0 + fr) * 64 + fq * 8;
;         const bf16x8 qf0 = *(const bf16x8*)qp, qf1 = *(const bf16x8*)(qp + 32);
;         for (int u = tid; u < 465; u += NTHREADS) rp[u] = p.rpb[h * 465 + u] * 1.4426950408889634f;
;         { const int t = tid >> 3, c = tid & 7; const unsigned dstk = (unsigned)(t * 128 + ((c ^ (((t >> 1) & 1) | (((t >> 3) & 3) << 1))) << 4)), dstv = (unsigned)(t * 128 + ((c ^ ((t >> 1) & 7)) << 4));
;           u32x4 kv[9], vv[9];
; #pragma unroll
;           for (int j = 0; j < 9; ++j) { const int srow = min(R0 + j, 31);
;               kv[j] = *(const u32x4*)(KH + ((size_t)(b * 8 + h) * SEQ + srow * 64 + t) * 64 + c * 8);
;               vv[j] = *(const u32x4*)(VTA + ((size_t)((b * 8 + h) * 32 + srow) * 64 + t) * 64 + c * 8); }
; #pragma unroll
.LBB0_335:
	s_waitcnt lgkmcnt(0)
	s_add_u32 s12, s34, 0x180000
	s_addc_u32 s13, s35, 0
	v_readfirstlane_b32 s0, v170
	s_and_b32 s98, s2, 7
	s_lshl_b32 s98, s98, 8
	s_add_u32 s14, s34, 0x8c000
	s_addc_u32 s15, s35, 0
	s_add_u32 s14, s14, s98
	s_addc_u32 s15, s15, 0
	s_lshr_b32 s10, s0, 8
	s_lshr_b32 s0, s0, 2
	s_and_b32 s0, s0, 48
	v_sub_u32_e64 v0, s0, 8 clamp
	v_min_u32_e32 v4, 32, v0
	v_lshlrev_b32_e32 v0, 1, v170
	v_and_b32_e32 v1, 3, v170
	v_mov_b32_e32 v31, 0
	v_lshlrev_b32_e32 v30, 1, v130
	v_and_or_b32 v5, v0, 24, v1
	v_or_b32_e32 v28, s0, v131
	v_lshl_add_u64 v[0:1], s[34:35], 0, v[30:31]
	s_mov_b64 s[0:1], 0x5f00000
	v_lshl_add_u64 v[32:33], v[0:1], 0, s[0:1]
	v_and_b32_e32 v1, 7, v170
	v_bfe_u32 v2, v170, 4, 1
	v_and_b32_e32 v3, 6, v133
	v_bitop3_b32 v2, v2, v1, v3 bitop3:0x36
	v_lshlrev_b32_e32 v6, 4, v2
	v_xor_b32_e32 v2, v172, v170
	v_lshlrev_b32_e32 v2, 4, v2
	v_lshlrev_b32_e32 v30, 4, v1
	v_lshlrev_b32_e32 v0, 7, v128
	v_and_b32_e32 v7, 0x70, v2
	v_lshl_add_u64 v[2:3], s[34:35], 0, v[30:31]
	s_mov_b64 s[4:5], 0x6f00000
	v_mov_b32_e32 v1, v31
	v_lshl_add_u64 v[34:35], v[2:3], 0, s[4:5]
	v_lshl_add_u64 v[2:3], s[34:35], 0, v[0:1]
	v_lshl_add_u64 v[2:3], v[2:3], 0, v[30:31]
	s_mov_b64 s[4:5], 0x7f00000
	v_add_u32_e32 v1, v4, v5
	v_lshl_add_u64 v[36:37], v[2:3], 0, s[4:5]
	v_lshrrev_b32_e32 v3, 2, v1
	v_bfe_u32 v2, v170, 1, 1
	v_and_b32_e32 v3, 6, v3
	v_bitop3_b32 v5, v3, v129, v2 bitop3:0x36
	v_lshlrev_b32_e32 v39, 4, v5
	v_or_b32_e32 v5, 4, v129
	s_add_i32 s4, 0, 0x12000
	v_bitop3_b32 v2, v3, v5, v2 bitop3:0x36
	v_add_u32_e32 v3, v4, v130
	v_lshrrev_b32_e32 v4, 3, v4
	v_add3_u32 v29, 0, v0, v6
	v_add3_u32 v38, s4, v0, v7
	v_lshrrev_b32_e32 v0, 1, v170
	v_lshlrev_b32_e32 v40, 4, v2
	v_sub_u32_e64 v2, v28, 8 clamp
	v_add_u32_e32 v4, v4, v129
	v_min_u32_e32 v2, 48, v2
	v_bitop3_b32 v0, v4, v0, 7 bitop3:0x78
	v_add_u32_e32 v5, 16, v2
	v_lshlrev_b32_e32 v6, 7, v131
	v_lshlrev_b32_e32 v0, 4, v0
	s_add_i32 s6, 0, 0x24000
	v_add3_u32 v41, s4, v6, v0
	v_lshl_add_u32 v42, v170, 2, s6
	v_cmp_ge_u32_e32 vcc, v3, v2
	v_cmp_lt_u32_e64 s[6:7], v3, v5
	v_sub_u32_e32 v6, v3, v28
	v_mov_b32_e32 v4, 0xf149f2ca
	s_and_b64 s[6:7], vcc, s[6:7]
	v_med3_i32 v46, v6, -15, 15
	v_or_b32_e32 v6, 1, v3
	v_cndmask_b32_e64 v45, v4, 0, s[6:7]
	v_cmp_ge_u32_e32 vcc, v6, v2
	v_cmp_lt_u32_e64 s[6:7], v6, v5
	v_sub_u32_e32 v6, v6, v28
	s_and_b64 s[6:7], vcc, s[6:7]
	v_med3_i32 v48, v6, -15, 15
	v_or_b32_e32 v6, 2, v3
	v_cndmask_b32_e64 v47, v4, 0, s[6:7]
	v_cmp_ge_u32_e32 vcc, v6, v2
	v_cmp_lt_u32_e64 s[6:7], v6, v5
	v_sub_u32_e32 v6, v6, v28
	s_and_b64 s[6:7], vcc, s[6:7]
	v_med3_i32 v50, v6, -15, 15
	v_or_b32_e32 v6, 3, v3
	v_cndmask_b32_e64 v49, v4, 0, s[6:7]
	v_cmp_ge_u32_e32 vcc, v6, v2
	v_cmp_lt_u32_e64 s[6:7], v6, v5
	v_sub_u32_e32 v6, v6, v28
	s_and_b64 s[6:7], vcc, s[6:7]
	v_med3_i32 v52, v6, -15, 15
	v_or_b32_e32 v6, 4, v3
	v_cndmask_b32_e64 v51, v4, 0, s[6:7]
	v_cmp_ge_u32_e32 vcc, v6, v2
	v_cmp_lt_u32_e64 s[6:7], v6, v5
	v_sub_u32_e32 v6, v6, v28
	s_and_b64 s[6:7], vcc, s[6:7]
	v_med3_i32 v54, v6, -15, 15
	v_or_b32_e32 v6, 5, v3
	v_cndmask_b32_e64 v53, v4, 0, s[6:7]
	v_cmp_ge_u32_e32 vcc, v6, v2
	v_cmp_lt_u32_e64 s[6:7], v6, v5
	v_sub_u32_e32 v6, v6, v28
	s_and_b64 s[6:7], vcc, s[6:7]
	v_med3_i32 v56, v6, -15, 15
	v_or_b32_e32 v6, 6, v3
	v_cndmask_b32_e64 v55, v4, 0, s[6:7]
	v_cmp_ge_u32_e32 vcc, v6, v2
	v_cmp_lt_u32_e64 s[6:7], v6, v5
	s_and_b64 s[6:7], vcc, s[6:7]
	v_or_b32_e32 v3, 7, v3
	v_lshlrev_b32_e32 v0, 2, v129
	v_cndmask_b32_e64 v57, v4, 0, s[6:7]
	v_cmp_ge_u32_e32 vcc, v3, v2
	v_cmp_lt_u32_e64 s[6:7], v3, v5
	s_movk_i32 s0, 0x1d1
	v_sub_u32_e32 v6, v6, v28
	s_and_b64 s[6:7], vcc, s[6:7]
	v_sub_u32_e32 v2, v3, v28
	v_lshlrev_b32_e32 v30, 1, v0
	v_mbcnt_lo_u32_b32 v0, -1, 0
	v_cmp_gt_u32_e64 s[0:1], s0, v170
	s_mov_b32 s17, 0
	v_cmp_eq_u32_e64 s[4:5], 0, v129
	v_add_u32_e32 v43, 0x10000, v29
	v_add_u32_e32 v44, 0x10000, v38
	s_mov_b32 s11, 0xf149f2ca
	v_med3_i32 v58, v6, -15, 15
	v_cndmask_b32_e64 v59, v4, 0, s[6:7]
	v_med3_i32 v60, v2, -15, 15
	v_lshl_add_u32 v61, v1, 7, 0
	s_add_i32 s33, 0, 0x24800
	s_movk_i32 s40, 0x7f
	s_mov_b64 s[6:7], 0xb200400
	s_mov_b32 s41, 0xb200000
	v_mbcnt_hi_u32_b32 v62, -1, v0
	s_and_saveexec_b64 s[98:99], s[58:59]
	s_cbranch_execz .Lattn_pf_a
	v_mov_b32_e32 v243, 1
	global_atomic_add v242, v31, v243, s[14:15] sc0

; __device__ __forceinline__ void attn_phase(const Params& p, LAS unsigned char* lds) {
;     ...
;         if (tid == 0) slot[0] = __hip_atomic_fetch_add(ctr, 1u, __ATOMIC_RELAXED, __HIP_MEMORY_SCOPE_AGENT);
;         __syncthreads();
;         const int item = (int)slot[0];
;         if (item >= 1024) break;
;         const int b = item >> 7, h = (item >> 4) & 7, r0 = (item & 15) * 2, R0 = min(max(r0 - 4, 0), 24);
;         const int r = r0 + ri, rs = min(max(r - 4, 0), 24), j0 = rs - R0;
;         const int tq = b * SEQ + r * 64 + q0 + fr;
;         const bf16_t* qp = QH + ((size_t)(b * 8 + h) * SEQ + r * 64 + q0 + fr) * 64 + fq * 8;
;         const bf16x8 qf0 = *(const bf16x8*)qp, qf1 = *(const bf16x8*)(qp + 32);
;         for (int u = tid; u < 465; u += NTHREADS) rp[u] = p.rpb[h * 465 + u] * 1.4426950408889634f;
.LBB0_342:
	s_or_b64 exec, exec, s[20:21]
	v_mov_b32_e32 v0, s33
	s_waitcnt lgkmcnt(0)
	s_barrier
	ds_read_b32 v0, v0
	s_mov_b64 s[20:21], -1
	s_waitcnt lgkmcnt(0)
	v_cmp_lt_i32_e32 vcc, s40, v0
	v_readfirstlane_b32 s16, v0
	s_cbranch_vccnz .LBB0_337
	s_and_b32 s43, s2, 7
	s_bfe_u32 s42, s16, 0x30004
	s_lshl_b32 s16, s16, 1
	s_lshl_b32 s20, s43, 3
	s_and_b32 s16, s16, 30
	s_or_b32 s20, s20, s42
	s_add_i32 s45, s16, s10
	s_ashr_i32 s21, s20, 31
	s_lshl_b32 s44, s45, 6
	s_lshl_b64 s[26:27], s[20:21], 11
	s_add_u32 s21, s26, s44
	s_addc_u32 s38, s27, 0
	v_mov_b32_e32 v1, s38
	v_or_b32_e32 v0, s21, v28
	v_lshlrev_b64 v[0:1], 7, v[0:1]
	v_lshl_add_u64 v[0:1], v[32:33], 0, v[0:1]
	global_load_dwordx4 v[12:15], v[0:1], off
	global_load_dwordx4 v[4:7], v[0:1], off offset:64
	s_and_saveexec_b64 s[38:39], s[0:1]
	s_cbranch_execz .LBB0_345
	s_mul_i32 s21, s42, 0x1d1
	v_add_lshl_u32 v0, s21, v170, 2
	global_load_dword v241, v0, s[50:51]
